# GEMM prologues: K-tile 1 staging DMAs issued before the first wait/barrier pair (latency overlapped with K-tile 0), stagger barrier moved behind them
# baseline (speedup 1.0000x reference)
.LBB0_138:
	s_ashr_i32 s0, s10, 8
	s_cmp_eq_u32 s0, 1
	s_cselect_b64 s[6:7], -1, 0
	v_lshl_add_u64 v[8:9], s[4:5], 0, v[146:147]
	v_lshl_add_u64 v[2:3], s[4:5], 0, v[150:151]
	v_lshl_add_u64 v[0:1], s[2:3], 0, v[144:145]
	v_writelane_b32 v254, s6, 19
	s_cmp_lg_u32 s0, 1
	v_lshl_add_u64 v[6:7], s[2:3], 0, v[148:149]
	v_writelane_b32 v254, s7, 20
	s_cselect_b32 s101, 0, 1

.LBB0_140:
	s_add_u32 s14, s28, 0x4300000
	s_addc_u32 s15, s29, 0
	s_add_u32 s18, s28, 0x6300000
	s_addc_u32 s19, s29, 0
	s_add_u32 s52, s28, 0x8400000
	s_addc_u32 s53, s29, 0
	s_add_u32 s54, s28, 0xa500000
	s_mov_b64 s[56:57], 0x80
	s_addc_u32 s55, s29, 0
	s_and_b32 s94, s11, 3
	s_add_i32 m0, s68, 0x18000
	v_lshl_add_u64 v[8:9], v[8:9], 0, s[56:57]
	s_lshl_b32 s95, s0, 6
	s_lshl_b32 s6, s0, 13
	s_lshl_b32 s7, s94, 12


	global_load_lds_dwordx4 v[8:9], off
	v_lshl_add_u64 v[2:3], v[2:3], 0, s[56:57]
	s_add_i32 m0, s68, 0x1a000
	s_add_i32 s96, s68, 0x8000
	s_add_i32 s71, s68, 0xa000
	global_load_lds_dwordx4 v[2:3], off
	v_lshl_add_u64 v[0:1], v[0:1], 0, s[56:57]
	s_mov_b32 m0, s96
	s_add_u32 s0, s4, 0x40080
	global_load_lds_dwordx4 v[0:1], off
	v_lshl_add_u64 v[0:1], v[6:7], 0, s[56:57]
	s_mov_b32 m0, s71
	s_addc_u32 s1, s5, 0
	global_load_lds_dwordx4 v[0:1], off
	s_add_i32 m0, s68, 0x1c000
	v_lshl_add_u64 v[0:1], s[0:1], 0, v[146:147]
	global_load_lds_dwordx4 v[0:1], off
	v_lshl_add_u64 v[0:1], s[0:1], 0, v[150:151]
	s_add_i32 m0, s68, 0x1e000
	s_cmpk_lt_u32 s10, 0x100
	global_load_lds_dwordx4 v[0:1], off
	s_cselect_b32 s100, 1, 0
	s_cmp_eq_u32 s101, 0
	s_cbranch_scc1 .Lpk1_FOXIN
	s_barrier
.Lpk1_FOXIN:
	s_waitcnt vmcnt(8)
	s_barrier
	s_cmp_lg_u32 s100, 0
	v_bfe_u32 v0, v26, 4, 2
	v_lshlrev_b32_e32 v154, 4, v0
	v_lshlrev_b32_e32 v152, 3, v0
	v_lshl_or_b32 v0, v153, 6, v154
	v_and_b32_e32 v1, 32, v4
	v_bitop3_b32 v2, v0, s6, v1 bitop3:0xde
	v_bitop3_b32 v167, v0, s7, v1 bitop3:0xde
	v_lshlrev_b32_e32 v0, 14, v27
	v_and_b32_e32 v0, 0xffff8000, v0
	v_lshl_add_u32 v0, v28, 11, v0
	v_and_b32_e32 v1, 1, v27
	v_lshl_or_b32 v0, v1, 6, v0
	v_lshl_add_u32 v158, v29, 1, v0
	v_lshlrev_b32_e32 v0, 14, v30
	v_and_b32_e32 v0, 0xffff8000, v0
	v_lshl_add_u32 v0, v31, 11, v0
	v_and_b32_e32 v1, 1, v30
	s_waitcnt vmcnt(6)
	v_lshl_or_b32 v0, v1, 6, v0
	s_cselect_b64 s[58:59], -1, 0
	v_mov_b32_e32 v155, 0
	v_lshl_add_u32 v160, v32, 1, v0
	s_add_i32 s72, 0, 0x10000
	s_add_i32 s73, 0, 0x14000
	v_mbcnt_lo_u32_b32 v0, -1, 0
	s_mov_b32 s76, 0
	s_ashr_i32 s10, s17, 31
	s_ashr_i32 s11, s16, 31
	v_lshl_add_u64 v[156:157], s[74:75], 0, v[154:155]
	v_mov_b32_e32 v159, v155
	v_mov_b32_e32 v161, v155
	v_mov_b64_e32 v[162:163], 0x400
	v_mov_b64_e32 v[164:165], 0x3ff
	v_add_u32_e32 v214, s72, v167
	v_add_u32_e32 v215, s73, v167
	v_add_u32_e32 v216, 0, v2
	v_mbcnt_hi_u32_b32 v217, -1, v0
	v_lshlrev_b32_e32 v218, 2, v152
	s_mov_b32 s60, 0x3a800000
	s_mov_b32 s12, 0x800000
	v_mov_b32_e32 v166, 0x358637bd
	v_mov_b32_e32 v219, 0x3e38aa3b
	s_waitcnt vmcnt(6)
	v_add_f32_e32 v240, v241, v240
	v_add_f32_e32 v241, v242, v243
	v_add_f32_e32 v244, v245, v244
	v_add_f32_e32 v245, v246, v247
	v_add_f32_e32 v242, v244, v245
	v_add_f32_e32 v243, v240, v241
	ds_bpermute_b32 v247, v238, v243
	ds_bpermute_b32 v246, v238, v242
	s_waitcnt lgkmcnt(0)
	v_pk_add_f32 v[250:251], v[242:243], v[246:247]
	ds_bpermute_b32 v253, v239, v251
	ds_bpermute_b32 v252, v239, v250
	s_waitcnt lgkmcnt(0)
	v_pk_add_f32 v[250:251], v[250:251], v[252:253]
	s_lshl_b32 s99, s98, 7
	v_lshl_add_u32 v236, v233, 2, s99
	v_add_u32_e32 v236, 0x22800, v236
	ds_write_b32 v236, v251
	ds_write_b32 v236, v250 offset:64
	v_add_u32_e32 v237, 0x22c00, v237
	ds_write_b32 v237, v248
	ds_write_b32 v237, v249 offset:256
	s_waitcnt lgkmcnt(0)
	s_barrier
	s_branch .LBB0_143

.LBB0_730:
	v_ashrrev_i32_e32 v2, 31, v0
	v_lshrrev_b32_e32 v2, 26, v2
	v_lshlrev_b32_e32 v1, 4, v0
	v_add_u32_e32 v2, v0, v2
	v_bfe_i32 v0, v0, 27, 1
	v_lshrrev_b32_e32 v0, 22, v0
	v_add_u32_e32 v0, v1, v0
	v_and_b32_e32 v0, 0xfffffc00, v0
	v_sub_u32_e32 v0, v1, v0
	v_ashrrev_i32_e32 v9, 6, v2
	v_lshrrev_b32_e32 v2, 4, v0
	v_bitop3_b32 v0, v2, v0, 32 bitop3:0x6c
	v_ashrrev_i32_e32 v3, 31, v0
	v_lshrrev_b32_e32 v3, 26, v3
	v_add_u32_e32 v3, v0, v3
	v_lshlrev_b32_e32 v2, 3, v9
	v_ashrrev_i32_e32 v10, 6, v3
	v_and_b32_e32 v3, 0xc0, v3
	v_and_b32_e32 v2, -16, v2
	v_sub_u32_e32 v0, v0, v3
	v_mov_b32_e32 v3, 1
	v_add_u32_e32 v2, v10, v2
	v_ashrrev_i16_sdwa v0, v3, sext(v0) dst_sel:DWORD dst_unused:UNUSED_PAD src0_sel:DWORD src1_sel:BYTE_0
	v_lshlrev_b32_e32 v4, 5, v9
	v_bfe_i32 v11, v0, 0, 16
	v_lshlrev_b32_e32 v0, 1, v2
	v_lshrrev_b32_e32 v5, 2, v2
	v_and_b32_e32 v6, 3, v10
	s_mov_b32 s7, 0x1fffe0
	v_and_b32_e32 v4, 32, v4
	v_and_b32_e32 v0, 24, v0
	v_and_b32_e32 v5, 4, v5
	v_and_or_b32 v6, v2, s7, v6
	v_or3_b32 v0, v6, v5, v0
	v_add_lshl_u32 v4, v4, v11, 1
	v_lshl_add_u32 v154, v0, 11, v4
	v_add_u32_e32 v0, 0x2000, v1
	v_ashrrev_i32_e32 v1, 31, v0
	v_lshrrev_b32_e32 v1, 22, v1
	v_add_u32_e32 v1, v0, v1
	v_ashrrev_i32_e32 v12, 10, v1
	v_mul_i32_i24_e32 v1, 0x400, v12
	v_sub_u32_e32 v0, v0, v1
	v_lshrrev_b32_e32 v1, 4, v0
	v_bitop3_b32 v0, v1, v0, 32 bitop3:0x6c
	s_add_u32 s41, s28, 0x4300000
	v_lshl_add_u32 v152, v2, 11, v4
	v_ashrrev_i32_e32 v2, 31, v0
	s_addc_u32 s54, s29, 0
	v_lshrrev_b32_e32 v2, 26, v2
	s_add_u32 s55, s28, 0x4100000
	v_add_u32_e32 v2, v0, v2
	s_addc_u32 s56, s29, 0
	s_ashr_i32 s6, s40, 6
	v_lshlrev_b32_e32 v1, 3, v12
	v_ashrrev_i32_e32 v13, 6, v2
	v_and_b32_e32 v2, 0xc0, v2
	v_and_b32_e32 v1, -16, v1
	v_sub_u32_e32 v0, v0, v2
	s_ashr_i32 s10, s40, 8
	s_lshl_b32 s57, s6, 10
	v_add_u32_e32 v1, v13, v1
	v_ashrrev_i16_sdwa v0, v3, sext(v0) dst_sel:DWORD dst_unused:UNUSED_PAD src0_sel:DWORD src1_sel:BYTE_0
	s_add_u32 s58, s55, s2
	v_lshlrev_b32_e32 v4, 5, v12
	v_bfe_i32 v14, v0, 0, 16
	v_lshlrev_b32_e32 v0, 1, v1
	v_lshrrev_b32_e32 v2, 2, v1
	v_and_b32_e32 v3, 3, v13
	s_addc_u32 s59, s56, s3
	s_add_i32 s62, s57, 0
	v_and_b32_e32 v4, 32, v4
	v_and_b32_e32 v0, 24, v0
	v_and_b32_e32 v2, 4, v2
	v_and_or_b32 v3, v1, s7, v3
	s_add_i32 m0, s62, 0x10000
	v_or3_b32 v0, v3, v2, v0
	v_add_lshl_u32 v2, v4, v14, 1
	global_load_lds_dwordx4 v154, s[58:59]
	s_add_i32 m0, s62, 0x12000
	v_lshl_add_u32 v158, v0, 11, v2
	s_add_u32 s2, s58, 0x40000
	global_load_lds_dwordx4 v158, s[58:59]
	s_addc_u32 s3, s59, 0
	s_add_i32 m0, s62, 0x14000
	v_lshl_add_u32 v156, v1, 11, v2
	global_load_lds_dwordx4 v154, s[2:3]
	s_add_i32 m0, s62, 0x16000
	s_add_u32 s52, s41, s0
	s_addc_u32 s53, s54, s1
	s_add_i32 s63, s62, 0x2000
	global_load_lds_dwordx4 v158, s[2:3]
	s_mov_b32 m0, s62
	s_add_u32 s0, s52, 0x40000
	global_load_lds_dwordx4 v152, s[52:53]
	s_mov_b32 m0, s63
	s_addc_u32 s1, s53, 0
	s_add_i32 s64, s62, 0x4000
	global_load_lds_dwordx4 v156, s[52:53]
	s_mov_b32 m0, s64
	s_add_i32 s65, s62, 0x6000
	global_load_lds_dwordx4 v152, s[0:1]
	s_mov_b32 m0, s65
	v_mov_b32_e32 v155, 0
	global_load_lds_dwordx4 v156, s[0:1]
	v_mov_b32_e32 v159, v155
	v_mov_b32_e32 v153, v155
	v_mov_b32_e32 v157, v155
	s_mov_b32 s7, 0
	v_lshl_add_u64 v[6:7], s[58:59], 0, v[154:155]
	v_lshl_add_u64 v[4:5], s[58:59], 0, v[158:159]
	v_lshl_add_u64 v[2:3], s[52:53], 0, v[152:153]
	s_cmp_lg_u32 s10, 1
	v_lshl_add_u64 v[0:1], s[52:53], 0, v[156:157]
	s_cselect_b32 s101, 0, 1

.LBB0_732:
	s_mov_b64 s[8:9], 0x80
	s_and_b32 s66, s6, 3
	s_add_i32 m0, s62, 0x18000
	v_lshl_add_u64 v[6:7], v[6:7], 0, s[8:9]
	s_lshl_b32 s2, s10, 13
	s_lshl_b32 s3, s66, 12


	global_load_lds_dwordx4 v[6:7], off
	v_lshl_add_u64 v[4:5], v[4:5], 0, s[8:9]
	s_add_i32 m0, s62, 0x1a000
	s_add_i32 s67, s62, 0x8000
	s_add_i32 s68, s62, 0xa000
	global_load_lds_dwordx4 v[4:5], off
	v_lshl_add_u64 v[2:3], v[2:3], 0, s[8:9]
	s_mov_b32 m0, s67
	s_add_u32 s0, s58, 0x40080
	global_load_lds_dwordx4 v[2:3], off
	v_lshl_add_u64 v[0:1], v[0:1], 0, s[8:9]
	s_mov_b32 m0, s68
	s_addc_u32 s1, s59, 0
	global_load_lds_dwordx4 v[0:1], off
	s_add_i32 m0, s62, 0x1c000
	v_lshl_add_u64 v[0:1], s[0:1], 0, v[154:155]
	global_load_lds_dwordx4 v[0:1], off
	v_lshl_add_u64 v[0:1], s[0:1], 0, v[158:159]
	s_add_i32 m0, s62, 0x1e000
	s_add_i32 s71, 0, 0x10000
	global_load_lds_dwordx4 v[0:1], off
	s_cselect_b32 s100, 1, 0
	s_cmp_eq_u32 s101, 0
	s_cbranch_scc1 .Lpk1_FOXOUT
	s_barrier
.Lpk1_FOXOUT:
	s_waitcnt vmcnt(8)
	s_barrier
	s_cmp_lg_u32 s100, 0
	v_bfe_u32 v1, v8, 4, 2
	v_and_b32_e32 v0, 15, v8
	v_lshlrev_b32_e32 v3, 4, v1
	v_lshl_or_b32 v184, s10, 6, v0
	v_lshl_or_b32 v0, v0, 6, v3
	v_lshlrev_b32_e32 v3, 2, v8
	v_and_b32_e32 v3, 32, v3
	v_bitop3_b32 v4, v0, s2, v3 bitop3:0xde
	v_bitop3_b32 v185, v0, s3, v3 bitop3:0xde
	v_lshlrev_b32_e32 v0, 14, v9
	v_and_b32_e32 v0, 0xffff8000, v0
	v_lshlrev_b32_e32 v2, 3, v1
	v_cmp_eq_u32_e64 s[0:1], 0, v1
	v_lshl_add_u32 v0, v10, 11, v0
	v_and_b32_e32 v1, 1, v9
	v_lshl_or_b32 v0, v1, 6, v0
	v_lshl_add_u32 v160, v11, 1, v0
	v_lshlrev_b32_e32 v0, 14, v12
	v_and_b32_e32 v0, 0xffff8000, v0
	v_lshl_add_u32 v0, v13, 11, v0
	v_and_b32_e32 v1, 1, v12
	s_waitcnt vmcnt(6)
	v_lshl_or_b32 v0, v1, 6, v0
	v_lshl_add_u32 v162, v14, 1, v0
	s_add_i32 s72, 0, 0x14000
	v_mbcnt_lo_u32_b32 v0, -1, 0
	v_lshl_or_b32 v186, s66, 5, v2
	s_ashr_i32 s69, s17, 31
	s_ashr_i32 s70, s16, 31
	v_mov_b32_e32 v161, v155
	v_mov_b32_e32 v163, v155
	v_mov_b64_e32 v[164:165], 0x100
	v_mov_b64_e32 v[166:167], 0xff
	v_add_u32_e32 v187, s71, v185
	v_add_u32_e32 v188, s72, v185
	v_add_u32_e32 v189, 0, v4
	v_mbcnt_hi_u32_b32 v190, -1, v0
	s_mov_b32 s73, 0
	s_barrier
	s_branch .LBB0_734

.LBB0_859:
	v_ashrrev_i32_e32 v1, 31, v30
	v_lshrrev_b32_e32 v1, 26, v1
	v_add_u32_e32 v1, v30, v1
	v_ashrrev_i32_e32 v10, 6, v1
	v_bfe_i32 v1, v30, 27, 1
	v_lshlrev_b32_e32 v0, 4, v30
	v_lshrrev_b32_e32 v1, 22, v1
	v_add_u32_e32 v1, v0, v1
	v_and_b32_e32 v1, 0xfffffc00, v1
	v_sub_u32_e32 v1, v0, v1
	v_lshrrev_b32_e32 v2, 4, v1
	v_bitop3_b32 v1, v2, v1, 32 bitop3:0x6c
	v_ashrrev_i32_e32 v3, 31, v1
	v_lshrrev_b32_e32 v3, 26, v3
	v_add_u32_e32 v3, v1, v3
	v_lshlrev_b32_e32 v2, 3, v10
	v_ashrrev_i32_e32 v11, 6, v3
	v_and_b32_e32 v3, 0xc0, v3
	v_and_b32_e32 v2, -16, v2
	v_sub_u32_e32 v1, v1, v3
	v_mov_b32_e32 v3, 1
	v_add_u32_e32 v2, v11, v2
	v_ashrrev_i16_sdwa v1, v3, sext(v1) dst_sel:DWORD dst_unused:UNUSED_PAD src0_sel:DWORD src1_sel:BYTE_0
	v_bfe_i32 v12, v1, 0, 16
	v_lshlrev_b32_e32 v1, 1, v2
	v_lshlrev_b32_e32 v6, 5, v10
	v_and_b32_e32 v13, 0x1fffe0, v2
	v_and_b32_e32 v14, 24, v1
	v_lshrrev_b32_e32 v1, 2, v2
	v_and_b32_e32 v16, 3, v11
	v_and_b32_e32 v6, 32, v6
	v_and_b32_e32 v15, 4, v1
	v_or_b32_e32 v1, v13, v16
	v_or3_b32 v1, v1, v15, v14
	v_add_lshl_u32 v6, v6, v12, 1
	v_add_u32_e32 v0, 0x2000, v0
	v_lshl_add_u32 v134, v1, 11, v6
	v_ashrrev_i32_e32 v1, 31, v0
	v_lshrrev_b32_e32 v1, 22, v1
	v_add_u32_e32 v1, v0, v1
	v_ashrrev_i32_e32 v17, 10, v1
	v_mul_i32_i24_e32 v1, 0x400, v17
	v_sub_u32_e32 v0, v0, v1
	v_lshrrev_b32_e32 v1, 4, v0
	v_bitop3_b32 v0, v1, v0, 32 bitop3:0x6c
	v_lshl_add_u32 v132, v2, 11, v6
	v_ashrrev_i32_e32 v2, 31, v0
	s_ashr_i32 s9, s5, 6
	s_ashr_i32 s8, s5, 8
	v_lshrrev_b32_e32 v2, 26, v2
	s_lshl_b32 s15, s9, 10
	v_add_u32_e32 v2, v0, v2
	s_add_u32 s19, s28, 0x2800000
	v_lshlrev_b32_e32 v1, 3, v17
	v_ashrrev_i32_e32 v6, 6, v2
	v_and_b32_e32 v2, 0xc0, v2
	s_addc_u32 s40, s29, 0
	s_lshl_b32 s2, s70, 8
	s_lshl_b32 s80, s57, 8
	v_and_b32_e32 v1, -16, v1
	v_sub_u32_e32 v0, v0, v2
	s_ashr_i32 s3, s2, 31
	s_ashr_i32 s81, s80, 31
	v_add_u32_e32 v1, v6, v1
	v_ashrrev_i16_sdwa v0, v3, sext(v0) dst_sel:DWORD dst_unused:UNUSED_PAD src0_sel:DWORD src1_sel:BYTE_0
	s_lshl_b64 s[6:7], s[2:3], 11
	s_lshl_b64 s[10:11], s[80:81], 11
	v_bfe_i32 v18, v0, 0, 16
	v_lshlrev_b32_e32 v0, 1, v1
	s_add_u32 s86, s19, s10
	v_lshlrev_b32_e32 v7, 5, v17
	v_and_b32_e32 v19, 0x1fffe0, v1
	v_and_b32_e32 v20, 24, v0
	v_lshrrev_b32_e32 v0, 2, v1
	v_and_b32_e32 v22, 3, v6
	s_addc_u32 s87, s40, s11
	s_add_i32 s41, s15, 0
	v_and_b32_e32 v7, 32, v7
	v_and_b32_e32 v21, 4, v0
	v_or_b32_e32 v0, v19, v22
	s_add_i32 m0, s41, 0x10000
	v_or3_b32 v0, v0, v21, v20
	v_add_lshl_u32 v2, v7, v18, 1
	global_load_lds_dwordx4 v134, s[86:87]
	s_add_i32 m0, s41, 0x12000
	v_lshl_add_u32 v138, v0, 11, v2
	s_add_u32 s10, s86, 0x40000
	global_load_lds_dwordx4 v138, s[86:87]
	s_addc_u32 s11, s87, 0
	s_add_i32 m0, s41, 0x14000
	v_lshl_add_u32 v136, v1, 11, v2
	global_load_lds_dwordx4 v134, s[10:11]
	s_add_i32 m0, s41, 0x16000
	s_add_u32 s84, s34, s6
	s_addc_u32 s85, s35, s7
	s_add_i32 s52, s41, 0x2000
	global_load_lds_dwordx4 v138, s[10:11]
	s_mov_b32 m0, s41
	s_add_u32 s6, s84, 0x40000
	global_load_lds_dwordx4 v132, s[84:85]
	s_mov_b32 m0, s52
	s_addc_u32 s7, s85, 0
	s_add_i32 s53, s41, 0x4000
	global_load_lds_dwordx4 v136, s[84:85]
	s_mov_b32 m0, s53
	s_add_i32 s54, s41, 0x6000
	global_load_lds_dwordx4 v132, s[6:7]
	s_mov_b32 m0, s54
	v_writelane_b32 v254, s62, 26
	global_load_lds_dwordx4 v136, s[6:7]
	s_nop 0
	v_writelane_b32 v254, s63, 27
	v_mov_b32_e32 v135, 0
	s_cmp_eq_u32 s8, 1
	v_writelane_b32 v254, s96, 28
	v_mov_b32_e32 v139, v135
	v_mov_b32_e32 v133, v135
	v_mov_b32_e32 v137, v135
	s_cselect_b64 s[6:7], -1, 0
	s_mov_b32 s4, 0
	v_lshl_add_u64 v[6:7], s[86:87], 0, v[134:135]
	v_lshl_add_u64 v[2:3], s[86:87], 0, v[138:139]
	v_lshl_add_u64 v[0:1], s[84:85], 0, v[132:133]
	v_writelane_b32 v254, s6, 29
	s_cmp_lg_u32 s8, 1
	v_lshl_add_u64 v[8:9], s[84:85], 0, v[136:137]
	v_writelane_b32 v254, s7, 30
	s_cselect_b32 s101, 0, 1

.LBB0_861:
	v_bfe_u32 v23, v5, 4, 2
	v_lshl_or_b32 v167, s8, 6, v4
	v_lshlrev_b32_e32 v24, 4, v23
	v_lshlrev_b32_e32 v5, 6, v4
	s_movk_i32 s3, 0x3c0
	v_lshlrev_b32_e32 v4, 2, v4
	v_and_or_b32 v25, v5, s3, v24
	s_lshl_b32 s3, s8, 13
	v_and_b32_e32 v4, 32, v4
	v_bitop3_b32 v26, v25, s3, v4 bitop3:0xde
	s_lshl_b32 s3, s9, 5
	s_and_b32 s3, s3, 0x60
	v_or_b32_e32 v5, v24, v5
	s_lshl_b32 s8, s3, 7
	v_bitop3_b32 v171, s8, v5, v4 bitop3:0xf6
	s_add_u32 s8, s28, 0x4300000
	s_mov_b64 s[10:11], 0x80
	s_addc_u32 s9, s29, 0
	s_add_i32 m0, s41, 0x18000
	v_lshl_add_u64 v[4:5], v[6:7], 0, s[10:11]


	global_load_lds_dwordx4 v[4:5], off
	v_lshl_add_u64 v[2:3], v[2:3], 0, s[10:11]
	s_add_i32 m0, s41, 0x1a000
	s_add_i32 s55, s41, 0x8000
	s_add_i32 s56, s41, 0xa000
	global_load_lds_dwordx4 v[2:3], off
	v_lshl_add_u64 v[0:1], v[0:1], 0, s[10:11]
	s_mov_b32 m0, s55
	s_add_u32 s12, s86, 0x40080
	global_load_lds_dwordx4 v[0:1], off
	v_lshl_add_u64 v[0:1], v[8:9], 0, s[10:11]
	s_mov_b32 m0, s56
	s_addc_u32 s13, s87, 0
	global_load_lds_dwordx4 v[0:1], off
	s_add_i32 m0, s41, 0x1c000
	v_lshl_add_u64 v[0:1], s[12:13], 0, v[134:135]
	global_load_lds_dwordx4 v[0:1], off
	v_lshl_add_u64 v[0:1], s[12:13], 0, v[138:139]
	s_add_i32 m0, s41, 0x1e000
	s_cmpk_lt_u32 s5, 0x100
	global_load_lds_dwordx4 v[0:1], off
	s_cselect_b32 s100, 1, 0
	s_cmp_eq_u32 s101, 0
	s_cbranch_scc1 .Lpk1_GATE0
	s_barrier
.Lpk1_GATE0:
	s_waitcnt vmcnt(8)
	s_barrier
	s_cmp_lg_u32 s100, 0
	v_add_u32_e32 v0, v13, v14
	v_and_b32_e32 v1, 1, v10
	s_cselect_b64 s[12:13], -1, 0
	v_lshl_or_b32 v175, v23, 3, s3
	s_and_b32 s3, s16, 7
	s_ashr_i32 s6, s16, 3
	v_add3_u32 v0, v0, v15, v16
	v_lshlrev_b32_e32 v1, 6, v1
	s_lshl_b32 s5, s3, 3
	s_and_b32 s14, s6, 7
	v_lshl_or_b32 v0, v0, 11, v1
	v_lshlrev_b32_e32 v2, 1, v12
	s_or_b32 s5, s5, s14
	v_add_u32_e32 v142, v0, v2
	v_add_u32_e32 v0, v19, v20
	v_and_b32_e32 v3, 1, v17
	v_writelane_b32 v254, s5, 31
	s_lshl_b32 s5, s5, 8
	v_add3_u32 v0, v0, v21, v22
	v_lshlrev_b32_e32 v3, 6, v3
	v_writelane_b32 v254, s5, 32
	s_lshl_b32 s5, s6, 7
	v_lshl_or_b32 v0, v0, 11, v3
	s_lshl_b32 s3, s3, 11
	s_and_b32 s5, s5, 0x780
	v_lshl_add_u32 v144, v18, 1, v0
	v_lshlrev_b32_e32 v0, 14, v10
	s_or_b32 s5, s5, s3
	s_lshr_b32 s3, s16, 7
	v_and_b32_e32 v0, 0xffff8000, v0
	s_mulk_i32 s3, 0x180
	v_lshl_add_u32 v0, v11, 11, v0
	s_waitcnt vmcnt(6)
	v_writelane_b32 v254, s6, 33
	s_addk_i32 s3, 0x800
	v_or_b32_e32 v0, v0, v1
	v_mov_b32_e32 v25, v135
	v_writelane_b32 v254, s3, 34
	v_add_u32_e32 v146, v0, v2
	s_add_i32 s76, 0, 0x10000
	s_add_i32 s77, 0, 0x14000
	v_mbcnt_lo_u32_b32 v0, -1, 0
	v_lshl_add_u64 v[140:141], s[74:75], 0, v[24:25]
	s_ashr_i32 s58, s17, 31
	s_ashr_i32 s59, s16, 31
	v_writelane_b32 v254, s5, 35
	s_lshr_b32 s3, s5, 8
	v_mov_b32_e32 v143, v135
	v_mov_b32_e32 v145, v135
	v_mov_b32_e32 v147, v135
	v_add_u32_e32 v182, s76, v171
	v_add_u32_e32 v183, s77, v171
	v_add_u32_e32 v184, 0, v26
	v_add_u32_e32 v185, 0, v171
	s_mov_b32 s14, 0x3a800000
	s_mov_b32 s18, 0x358637bd
	s_mov_b32 s81, 0x800000
	s_movk_i32 s94, 0x1600
	v_mov_b64_e32 v[148:149], 0x2bf
	v_mbcnt_hi_u32_b32 v186, -1, v0
	s_mov_b32 s69, 0
	s_barrier
	v_writelane_b32 v254, s3, 36
	s_branch .LBB0_864

.LBB0_963:
	v_ashrrev_i32_e32 v1, 31, v39
	v_lshrrev_b32_e32 v1, 26, v1
	v_add_u32_e32 v1, v39, v1
	v_ashrrev_i32_e32 v8, 6, v1
	v_bfe_i32 v1, v39, 27, 1
	v_lshlrev_b32_e32 v0, 4, v39
	v_lshrrev_b32_e32 v1, 22, v1
	v_add_u32_e32 v1, v0, v1
	v_and_b32_e32 v1, 0xfffffc00, v1
	v_sub_u32_e32 v1, v0, v1
	v_lshrrev_b32_e32 v2, 4, v1
	v_bitop3_b32 v1, v2, v1, 32 bitop3:0x6c
	v_ashrrev_i32_e32 v3, 31, v1
	v_lshrrev_b32_e32 v3, 26, v3
	v_add_u32_e32 v3, v1, v3
	v_lshlrev_b32_e32 v2, 3, v8
	v_ashrrev_i32_e32 v9, 6, v3
	v_and_b32_e32 v3, 0xc0, v3
	v_and_b32_e32 v2, -16, v2
	v_sub_u32_e32 v1, v1, v3
	v_mov_b32_e32 v3, 1
	v_add_u32_e32 v2, v9, v2
	v_ashrrev_i16_sdwa v1, v3, sext(v1) dst_sel:DWORD dst_unused:UNUSED_PAD src0_sel:DWORD src1_sel:BYTE_0
	v_lshlrev_b32_e32 v4, 5, v8
	v_bfe_i32 v10, v1, 0, 16
	v_lshlrev_b32_e32 v1, 1, v2
	v_lshrrev_b32_e32 v5, 2, v2
	v_and_b32_e32 v6, 3, v9
	s_mov_b32 s4, 0x1fffe0
	v_and_b32_e32 v4, 32, v4
	v_and_b32_e32 v1, 24, v1
	v_and_b32_e32 v5, 4, v5
	v_and_or_b32 v6, v2, s4, v6
	v_or3_b32 v1, v6, v5, v1
	v_add_lshl_u32 v4, v4, v10, 1
	v_add_u32_e32 v0, 0x2000, v0
	v_lshl_add_u32 v182, v1, 11, v4
	v_ashrrev_i32_e32 v1, 31, v0
	v_lshrrev_b32_e32 v1, 22, v1
	v_add_u32_e32 v1, v0, v1
	v_ashrrev_i32_e32 v11, 10, v1
	v_mul_i32_i24_e32 v1, 0x400, v11
	v_sub_u32_e32 v0, v0, v1
	v_lshrrev_b32_e32 v1, 4, v0
	v_bitop3_b32 v0, v1, v0, 32 bitop3:0x6c
	v_lshl_add_u32 v180, v2, 11, v4
	v_ashrrev_i32_e32 v2, 31, v0
	v_lshrrev_b32_e32 v2, 26, v2
	s_add_u32 s40, s28, 0x2d80000
	v_add_u32_e32 v2, v0, v2
	s_addc_u32 s41, s29, 0
	v_lshlrev_b32_e32 v1, 3, v11
	v_ashrrev_i32_e32 v12, 6, v2
	v_and_b32_e32 v2, 0xc0, v2
	s_ashr_i32 s18, s36, 6
	s_ashr_i32 s37, s36, 8
	v_and_b32_e32 v1, -16, v1
	v_sub_u32_e32 v0, v0, v2
	s_lshl_b32 s52, s18, 10
	v_add_u32_e32 v1, v12, v1
	v_ashrrev_i16_sdwa v0, v3, sext(v0) dst_sel:DWORD dst_unused:UNUSED_PAD src0_sel:DWORD src1_sel:BYTE_0
	s_add_u32 s6, s40, s2
	v_lshlrev_b32_e32 v4, 5, v11
	v_bfe_i32 v13, v0, 0, 16
	v_lshlrev_b32_e32 v0, 1, v1
	v_lshrrev_b32_e32 v2, 2, v1
	v_and_b32_e32 v3, 3, v12
	s_addc_u32 s7, s41, s3
	s_add_i32 s53, s52, 0
	v_and_b32_e32 v4, 32, v4
	v_and_b32_e32 v0, 24, v0
	v_and_b32_e32 v2, 4, v2
	v_and_or_b32 v3, v1, s4, v3
	s_add_i32 m0, s53, 0x10000
	v_or3_b32 v0, v3, v2, v0
	v_add_lshl_u32 v2, v4, v13, 1
	global_load_lds_dwordx4 v182, s[6:7]
	s_add_i32 m0, s53, 0x12000
	v_lshl_add_u32 v186, v0, 11, v2
	s_add_u32 s2, s6, 0x40000
	global_load_lds_dwordx4 v186, s[6:7]
	s_addc_u32 s3, s7, 0
	s_add_i32 m0, s53, 0x14000
	v_lshl_add_u32 v184, v1, 11, v2
	global_load_lds_dwordx4 v182, s[2:3]
	s_add_i32 m0, s53, 0x16000
	s_add_u32 s4, s34, s0
	s_addc_u32 s5, s35, s1
	s_add_i32 s54, s53, 0x2000
	global_load_lds_dwordx4 v186, s[2:3]
	s_mov_b32 m0, s53
	s_add_u32 s0, s4, 0x40000
	global_load_lds_dwordx4 v180, s[4:5]
	s_mov_b32 m0, s54
	s_addc_u32 s1, s5, 0
	s_add_i32 s55, s53, 0x4000
	global_load_lds_dwordx4 v184, s[4:5]
	s_mov_b32 m0, s55
	s_add_i32 s56, s53, 0x6000
	global_load_lds_dwordx4 v180, s[0:1]
	s_mov_b32 m0, s56
	v_mov_b32_e32 v183, 0
	global_load_lds_dwordx4 v184, s[0:1]
	v_mov_b32_e32 v187, v183
	v_mov_b32_e32 v181, v183
	v_mov_b32_e32 v185, v183
	s_cmp_eq_u32 s37, 1
	s_mov_b32 s57, 0
	v_lshl_add_u64 v[6:7], s[6:7], 0, v[182:183]
	v_lshl_add_u64 v[4:5], s[6:7], 0, v[186:187]
	v_lshl_add_u64 v[0:1], s[4:5], 0, v[180:181]
	s_cselect_b64 s[10:11], -1, 0
	s_cmp_lg_u32 s37, 1
	v_lshl_add_u64 v[2:3], s[4:5], 0, v[184:185]
	s_cselect_b32 s101, 0, 1

.LBB0_965:
	s_add_u32 s12, s28, 0x4300000
	s_addc_u32 s13, s29, 0
	s_add_u32 s14, s28, 0x9b00000
	s_addc_u32 s15, s29, 0
	s_lshl_b32 s0, s18, 5
	s_mov_b64 s[18:19], 0x80
	s_and_b32 s3, s0, 0x60
	s_add_i32 m0, s53, 0x18000
	v_lshl_add_u64 v[6:7], v[6:7], 0, s[18:19]
	s_lshl_b32 s2, s37, 13
	s_lshl_b32 s38, s3, 7


	global_load_lds_dwordx4 v[6:7], off
	v_lshl_add_u64 v[4:5], v[4:5], 0, s[18:19]
	s_add_i32 m0, s53, 0x1a000
	s_add_i32 s58, s53, 0x8000
	s_add_i32 s59, s53, 0xa000
	global_load_lds_dwordx4 v[4:5], off
	v_lshl_add_u64 v[0:1], v[0:1], 0, s[18:19]
	s_mov_b32 m0, s58
	s_add_u32 s0, s6, 0x40080
	global_load_lds_dwordx4 v[0:1], off
	v_lshl_add_u64 v[0:1], v[2:3], 0, s[18:19]
	s_mov_b32 m0, s59
	s_addc_u32 s1, s7, 0
	global_load_lds_dwordx4 v[0:1], off
	s_add_i32 m0, s53, 0x1c000
	v_lshl_add_u64 v[0:1], s[0:1], 0, v[182:183]
	global_load_lds_dwordx4 v[0:1], off
	v_lshl_add_u64 v[0:1], s[0:1], 0, v[186:187]
	s_add_i32 m0, s53, 0x1e000
	v_bfe_u32 v2, v38, 4, 2
	global_load_lds_dwordx4 v[0:1], off
	s_cselect_b32 s100, 1, 0
	s_cmp_eq_u32 s101, 0
	s_cbranch_scc1 .Lpk1_UP0
	s_barrier
.Lpk1_UP0:
	s_waitcnt vmcnt(8)
	s_barrier
	s_cmp_lg_u32 s100, 0
	v_and_b32_e32 v1, 15, v38
	v_lshlrev_b32_e32 v0, 4, v2
	v_lshl_or_b32 v234, s37, 6, v1
	v_lshl_or_b32 v3, v1, 6, v0
	v_cmp_lt_u32_e64 s[0:1], 13, v1
	v_mov_b32_e32 v1, v183
	v_lshl_add_u64 v[188:189], s[74:75], 0, v[0:1]
	v_lshlrev_b32_e32 v0, 14, v8
	v_and_b32_e32 v0, 0xffff8000, v0
	v_lshl_add_u32 v0, v9, 11, v0
	v_and_b32_e32 v1, 1, v8
	v_lshlrev_b32_e32 v4, 2, v38
	s_cmpk_lt_u32 s36, 0x100
	v_lshl_or_b32 v0, v1, 6, v0
	v_and_b32_e32 v4, 32, v4
	s_cselect_b64 s[36:37], -1, 0
	s_ashr_i32 s61, s17, 31
	s_ashr_i32 s63, s16, 31
	v_lshl_add_u32 v190, v10, 1, v0
	v_lshlrev_b32_e32 v0, 14, v11
	v_bitop3_b32 v235, s38, v3, v4 bitop3:0xf6
	s_add_u32 s38, s20, 0x2c00
	v_and_b32_e32 v0, 0xffff8000, v0
	s_addc_u32 s39, s21, 0
	v_lshl_add_u32 v0, v12, 11, v0
	v_and_b32_e32 v1, 1, v11
	s_waitcnt vmcnt(6)
	s_add_u32 s44, s20, 0x5800
	v_lshl_or_b32 v0, v1, 6, v0
	v_bitop3_b32 v5, v3, s2, v4 bitop3:0xde
	s_addc_u32 s45, s21, 0
	v_lshl_add_u32 v192, v13, 1, v0
	s_add_i32 s68, 0, 0x10000
	s_add_i32 s69, 0, 0x14000
	v_mbcnt_lo_u32_b32 v0, -1, 0
	v_lshl_or_b32 v236, v2, 3, s3
	v_mov_b32_e32 v191, v183
	v_mov_b32_e32 v193, v183
	v_mov_b64_e32 v[194:195], 0x2c0
	v_mov_b64_e32 v[196:197], 0x2bf
	v_add_u32_e32 v237, s68, v235
	v_add_u32_e32 v238, s69, v235
	v_add_u32_e32 v239, 0, v5
	v_mbcnt_hi_u32_b32 v240, -1, v0
	s_movk_i32 s70, 0x1600
	v_mov_b32_e32 v241, 0x358637bd
	s_mov_b32 s60, 0x3a800000
	s_mov_b32 s77, 0x800000
	s_mov_b32 s62, 0x358637bd
	s_barrier
	s_branch .LBB0_968

.LBB0_1065:
	s_ashr_i32 s0, s40, 8
	v_lshl_add_u64 v[8:9], s[38:39], 0, v[154:155]
	v_lshl_add_u64 v[6:7], s[38:39], 0, v[158:159]
	v_lshl_add_u64 v[2:3], s[36:37], 0, v[152:153]
	s_cmp_lg_u32 s0, 1
	v_lshl_add_u64 v[4:5], s[36:37], 0, v[156:157]
	s_cselect_b32 s101, 0, 1

.LBB0_1067:
	s_mov_b64 s[14:15], 0x80
	s_and_b32 s58, s4, 3
	s_add_i32 m0, s54, 0x18000
	v_lshl_add_u64 v[8:9], v[8:9], 0, s[14:15]
	s_lshl_b32 s1, s0, 13
	s_lshl_b32 s4, s58, 12


	global_load_lds_dwordx4 v[8:9], off
	v_lshl_add_u64 v[6:7], v[6:7], 0, s[14:15]
	s_add_i32 m0, s54, 0x1a000
	s_add_i32 s59, s54, 0x8000
	s_add_i32 s62, s54, 0xa000
	global_load_lds_dwordx4 v[6:7], off
	v_lshl_add_u64 v[2:3], v[2:3], 0, s[14:15]
	s_mov_b32 m0, s59
	s_add_u32 s2, s38, 0xb0080
	global_load_lds_dwordx4 v[2:3], off
	v_lshl_add_u64 v[2:3], v[4:5], 0, s[14:15]
	s_mov_b32 m0, s62
	s_addc_u32 s3, s39, 0
	global_load_lds_dwordx4 v[2:3], off
	s_add_i32 m0, s54, 0x1c000
	v_lshl_add_u64 v[2:3], s[2:3], 0, v[154:155]
	global_load_lds_dwordx4 v[2:3], off
	v_lshl_add_u64 v[2:3], s[2:3], 0, v[158:159]
	s_add_i32 m0, s54, 0x1e000
	v_bfe_u32 v1, v36, 4, 2
	global_load_lds_dwordx4 v[2:3], off
	s_cselect_b32 s100, 1, 0
	s_cmp_eq_u32 s101, 0
	s_cbranch_scc1 .Lpk1_DOWN0
	s_barrier
.Lpk1_DOWN0:
	s_waitcnt vmcnt(8)
	s_barrier
	s_cmp_lg_u32 s100, 0
	v_lshlrev_b32_e32 v3, 4, v1
	v_lshl_or_b32 v3, v45, 6, v3
	v_and_b32_e32 v0, 32, v0
	s_movk_i32 s6, 0xb00
	v_lshl_or_b32 v184, s0, 6, v45
	v_lshlrev_b32_e32 v2, 3, v1
	v_bitop3_b32 v4, v3, s1, v0 bitop3:0xde
	v_bitop3_b32 v185, v3, s4, v0 bitop3:0xde
	v_cmp_eq_u32_e64 s[0:1], 0, v1
	v_lshrrev_b32_e32 v1, 1, v37
	v_mul_lo_u32 v0, v39, s6
	s_mov_b32 s7, 0xb000
	v_mad_u64_u32 v[0:1], s[4:5], v1, s7, v[0:1]
	v_or_b32_e32 v0, v0, v38
	s_mov_b64 s[2:3], 0xb0080
	v_add_lshl_u32 v0, v0, v40, 1
	v_mov_b32_e32 v1, 0
	v_lshl_or_b32 v186, s58, 5, v2
	v_lshl_add_u64 v[160:161], v[0:1], 0, s[2:3]
	v_lshrrev_b32_e32 v2, 1, v41
	v_mul_lo_u32 v0, v42, s6
	v_mad_u64_u32 v[2:3], s[4:5], v2, s7, v[0:1]
	v_or_b32_e32 v0, v2, v43
	s_waitcnt vmcnt(6)
	v_add_lshl_u32 v0, v0, v44, 1
	v_lshl_add_u64 v[162:163], v[0:1], 0, s[2:3]
	s_add_i32 s65, 0, 0x10000
	s_add_i32 s66, 0, 0x14000
	v_mbcnt_lo_u32_b32 v0, -1, 0
	s_mov_b32 s19, 0
	s_ashr_i32 s63, s17, 31
	s_ashr_i32 s64, s16, 31
	v_mov_b64_e32 v[164:165], 0x100
	v_mov_b64_e32 v[166:167], 0xff
	v_add_u32_e32 v187, s65, v185
	v_add_u32_e32 v188, s66, v185
	v_add_u32_e32 v189, 0, v4
	v_mbcnt_hi_u32_b32 v190, -1, v0
	s_mov_b32 s67, 0
	s_barrier
	s_branch .LBB0_1069

.LBB0_1169:
	v_ashrrev_i32_e32 v1, 31, v28
	v_lshrrev_b32_e32 v1, 26, v1
	v_add_u32_e32 v1, v28, v1
	v_ashrrev_i32_e32 v5, 6, v1
	v_bfe_i32 v1, v28, 27, 1
	v_lshlrev_b32_e32 v0, 4, v28
	v_lshrrev_b32_e32 v1, 22, v1
	v_add_u32_e32 v1, v0, v1
	v_and_b32_e32 v1, 0xfffffc00, v1
	v_sub_u32_e32 v1, v0, v1
	v_lshrrev_b32_e32 v2, 4, v1
	v_bitop3_b32 v1, v2, v1, 32 bitop3:0x6c
	v_ashrrev_i32_e32 v3, 31, v1
	v_lshrrev_b32_e32 v3, 26, v3
	v_add_u32_e32 v3, v1, v3
	v_lshlrev_b32_e32 v2, 3, v5
	v_ashrrev_i32_e32 v10, 6, v3
	v_and_b32_e32 v3, 0xc0, v3
	v_and_b32_e32 v2, -16, v2
	v_sub_u32_e32 v1, v1, v3
	v_mov_b32_e32 v3, 1
	v_add_u32_e32 v2, v10, v2
	v_ashrrev_i16_sdwa v1, v3, sext(v1) dst_sel:DWORD dst_unused:UNUSED_PAD src0_sel:DWORD src1_sel:BYTE_0
	v_lshlrev_b32_e32 v6, 5, v5
	v_bfe_i32 v11, v1, 0, 16
	v_lshlrev_b32_e32 v1, 1, v2
	v_lshrrev_b32_e32 v7, 2, v2
	v_and_b32_e32 v8, 3, v10
	s_mov_b32 s1, 0x1fffe0
	v_and_b32_e32 v6, 32, v6
	v_and_b32_e32 v1, 24, v1
	v_and_b32_e32 v7, 4, v7
	v_and_or_b32 v8, v2, s1, v8
	v_or3_b32 v1, v8, v7, v1
	v_add_lshl_u32 v6, v6, v11, 1
	v_add_u32_e32 v0, 0x2000, v0
	v_lshl_add_u32 v134, v1, 11, v6
	v_ashrrev_i32_e32 v1, 31, v0
	v_lshrrev_b32_e32 v1, 22, v1
	v_add_u32_e32 v1, v0, v1
	v_ashrrev_i32_e32 v12, 10, v1
	v_mul_i32_i24_e32 v1, 0x400, v12
	v_sub_u32_e32 v0, v0, v1
	v_lshrrev_b32_e32 v1, 4, v0
	v_bitop3_b32 v0, v1, v0, 32 bitop3:0x6c
	v_lshl_add_u32 v132, v2, 11, v6
	v_ashrrev_i32_e32 v2, 31, v0
	v_lshrrev_b32_e32 v2, 26, v2
	v_add_u32_e32 v2, v0, v2
	v_lshlrev_b32_e32 v1, 3, v12
	v_ashrrev_i32_e32 v13, 6, v2
	v_and_b32_e32 v2, 0xc0, v2
	v_and_b32_e32 v1, -16, v1
	v_sub_u32_e32 v0, v0, v2
	v_add_u32_e32 v1, v13, v1
	v_ashrrev_i16_sdwa v0, v3, sext(v0) dst_sel:DWORD dst_unused:UNUSED_PAD src0_sel:DWORD src1_sel:BYTE_0
	v_and_b32_e32 v3, 3, v13
	v_and_or_b32 v3, v1, s1, v3
	s_ashr_i32 s1, s14, 6
	s_ashr_i32 s3, s3, 3
	s_ashr_i32 s0, s14, 8
	s_lshl_b32 s66, s1, 10
	s_add_u32 s67, s28, 0x3900000
	s_addc_u32 s78, s29, 0
	s_add_i32 s2, s2, s3
	s_ashr_i32 s3, s2, 31
	s_lshr_b32 s3, s3, 25
	s_add_i32 s3, s2, s3
	s_ashr_i32 s6, s3, 7
	s_and_b32 s3, s3, 0xffffff80
	s_sub_i32 s2, s2, s3
	s_bfe_i32 s3, s2, 0x80000
	s_bfe_u32 s3, s3, 0x3000c
	s_add_i32 s3, s2, s3
	s_bfe_i32 s7, s3, 0x80000
	s_and_b32 s3, s3, 0xf8
	s_sub_i32 s2, s2, s3
	s_lshl_b32 s6, s6, 3
	s_sext_i32_i16 s7, s7
	s_sext_i32_i8 s2, s2
	s_add_i32 s41, s6, s2
	s_ashr_i32 s40, s7, 3
	s_lshl_b32 s2, s40, 8
	s_lshl_b32 s6, s41, 8
	s_ashr_i32 s3, s2, 31
	s_ashr_i32 s7, s6, 31
	s_lshl_b64 s[2:3], s[2:3], 11
	s_lshl_b64 s[6:7], s[6:7], 11
	s_add_u32 s62, s67, s2
	v_lshlrev_b32_e32 v6, 5, v12
	v_bfe_i32 v14, v0, 0, 16
	v_lshlrev_b32_e32 v0, 1, v1
	v_lshrrev_b32_e32 v2, 2, v1
	s_addc_u32 s63, s78, s3
	s_add_i32 s79, s66, 0
	v_and_b32_e32 v6, 32, v6
	v_and_b32_e32 v0, 24, v0
	v_and_b32_e32 v2, 4, v2
	s_add_i32 m0, s79, 0x10000
	v_or3_b32 v0, v3, v2, v0
	v_add_lshl_u32 v2, v6, v14, 1
	global_load_lds_dwordx4 v134, s[62:63]
	s_add_i32 m0, s79, 0x12000
	v_lshl_add_u32 v138, v0, 11, v2
	s_add_u32 s2, s62, 0x40000
	global_load_lds_dwordx4 v138, s[62:63]
	s_addc_u32 s3, s63, 0
	s_add_i32 m0, s79, 0x14000
	v_lshl_add_u32 v136, v1, 11, v2
	global_load_lds_dwordx4 v134, s[2:3]
	s_add_i32 m0, s79, 0x16000
	v_mov_b32_e32 v141, 0
	global_load_lds_dwordx4 v138, s[2:3]
	s_add_u32 s2, s34, s6
	s_addc_u32 s3, s35, s7
	s_add_i32 s80, s79, 0x2000
	s_mov_b32 m0, s79
	s_add_u32 s6, s2, 0x40000
	global_load_lds_dwordx4 v132, s[2:3]
	s_mov_b32 m0, s80
	s_addc_u32 s7, s3, 0
	s_add_i32 s81, s79, 0x4000
	global_load_lds_dwordx4 v136, s[2:3]
	s_mov_b32 m0, s81
	s_add_i32 s82, s79, 0x6000
	global_load_lds_dwordx4 v132, s[6:7]
	s_mov_b32 m0, s82
	v_mov_b32_e32 v135, v141
	global_load_lds_dwordx4 v136, s[6:7]
	v_mov_b32_e32 v139, v141
	v_mov_b32_e32 v133, v141
	v_mov_b32_e32 v137, v141
	s_cmp_eq_u32 s0, 1
	s_mov_b32 s83, 0
	v_lshl_add_u64 v[8:9], s[62:63], 0, v[134:135]
	v_lshl_add_u64 v[6:7], s[62:63], 0, v[138:139]
	v_lshl_add_u64 v[0:1], s[2:3], 0, v[132:133]
	s_cselect_b64 s[6:7], -1, 0
	s_cmp_lg_u32 s0, 1
	v_lshl_add_u64 v[2:3], s[2:3], 0, v[136:137]
	s_cselect_b32 s101, 0, 1

.LBB0_1171:
	s_lshl_b32 s1, s1, 5
	s_and_b32 s1, s1, 0x60
	s_lshl_b32 s15, s0, 13
	s_lshl_b32 s18, s1, 7
	s_add_u32 s84, s28, 0x4300000
	s_addc_u32 s85, s29, 0
	s_add_u32 s8, s28, 0xa300000
	s_addc_u32 s9, s29, 0
	s_add_u32 s10, s28, 0x578000
	s_mov_b64 s[12:13], 0x80
	s_addc_u32 s11, s29, 0
	s_add_i32 m0, s79, 0x18000
	v_lshl_add_u64 v[8:9], v[8:9], 0, s[12:13]


	global_load_lds_dwordx4 v[8:9], off
	v_lshl_add_u64 v[6:7], v[6:7], 0, s[12:13]
	s_add_i32 m0, s79, 0x1a000
	s_add_i32 s86, s79, 0x8000
	s_add_i32 s87, s79, 0xa000
	global_load_lds_dwordx4 v[6:7], off
	v_lshl_add_u64 v[0:1], v[0:1], 0, s[12:13]
	s_mov_b32 m0, s86
	s_add_u32 s36, s62, 0x40080
	global_load_lds_dwordx4 v[0:1], off
	v_lshl_add_u64 v[0:1], v[2:3], 0, s[12:13]
	s_mov_b32 m0, s87
	s_addc_u32 s37, s63, 0
	global_load_lds_dwordx4 v[0:1], off
	s_add_i32 m0, s79, 0x1c000
	v_lshl_add_u64 v[0:1], s[36:37], 0, v[134:135]
	global_load_lds_dwordx4 v[0:1], off
	v_lshl_add_u64 v[0:1], s[36:37], 0, v[138:139]
	s_add_i32 m0, s79, 0x1e000
	v_and_b32_e32 v2, 32, v4
	global_load_lds_dwordx4 v[0:1], off
	s_cselect_b32 s100, 1, 0
	s_cmp_eq_u32 s101, 0
	s_cbranch_scc1 .Lpk1_HGIN
	s_barrier
.Lpk1_HGIN:
	s_waitcnt vmcnt(8)
	s_barrier
	s_cmp_lg_u32 s100, 0
	v_bfe_u32 v0, v26, 4, 2
	v_lshlrev_b32_e32 v140, 4, v0
	v_lshl_or_b32 v174, v0, 3, s1
	v_lshlrev_b32_e32 v0, 14, v5
	v_lshl_or_b32 v1, v27, 6, v140
	v_and_b32_e32 v0, 0xffff8000, v0
	v_bitop3_b32 v3, v1, s15, v2 bitop3:0xde
	v_bitop3_b32 v173, s18, v1, v2 bitop3:0xf6
	v_lshl_add_u32 v0, v10, 11, v0
	v_and_b32_e32 v1, 1, v5
	v_lshl_or_b32 v0, v1, 6, v0
	v_lshl_add_u32 v144, v11, 1, v0
	v_lshlrev_b32_e32 v0, 14, v12
	v_and_b32_e32 v0, 0xffff8000, v0
	v_lshl_add_u32 v0, v13, 11, v0
	v_and_b32_e32 v1, 1, v12
	s_waitcnt vmcnt(6)
	s_cmpk_lt_u32 s14, 0x100
	v_lshl_or_b32 v0, v1, 6, v0
	s_cselect_b64 s[14:15], -1, 0
	v_lshl_add_u32 v146, v14, 1, v0
	s_add_i32 s89, 0, 0x10000
	s_add_i32 s90, 0, 0x14000
	v_mbcnt_lo_u32_b32 v0, -1, 0
	v_lshl_or_b32 v172, s0, 6, v27
	s_ashr_i32 s88, s17, 31
	v_lshl_add_u64 v[142:143], s[74:75], 0, v[140:141]
	v_mov_b32_e32 v145, v141
	v_mov_b32_e32 v147, v141
	v_mov_b64_e32 v[148:149], 0x400
	v_mov_b64_e32 v[150:151], 0x3ff
	v_add_u32_e32 v175, s89, v173
	v_add_u32_e32 v176, s90, v173
	v_add_u32_e32 v177, 0, v3
	v_mbcnt_hi_u32_b32 v178, -1, v0
	s_mov_b32 s18, 0x3a800000
	s_mov_b32 s91, 0x800000
	s_mov_b32 s92, 0x3f317217
	s_mov_b32 s93, 0x7f800000
	v_mov_b32_e32 v179, 0x41b17218
	s_barrier
	s_branch .LBB0_1174

.LBB0_1519:
	s_ashr_i32 s0, s40, 8
	v_lshl_add_u64 v[8:9], s[36:37], 0, v[154:155]
	v_lshl_add_u64 v[6:7], s[36:37], 0, v[158:159]
	v_lshl_add_u64 v[0:1], s[24:25], 0, v[152:153]
	s_cmp_lg_u32 s0, 1
	v_lshl_add_u64 v[2:3], s[24:25], 0, v[156:157]
	s_cselect_b32 s101, 0, 1

.LBB0_1521:
	s_mov_b64 s[6:7], 0x80
	s_and_b32 s50, s9, 3
	s_add_i32 m0, s46, 0x18000
	v_lshl_add_u64 v[8:9], v[8:9], 0, s[6:7]
	s_lshl_b32 s1, s0, 13
	s_lshl_b32 s9, s50, 12


	global_load_lds_dwordx4 v[8:9], off
	v_lshl_add_u64 v[6:7], v[6:7], 0, s[6:7]
	s_add_i32 m0, s46, 0x1a000
	s_add_i32 s51, s46, 0x8000
	s_add_i32 s52, s46, 0xa000
	global_load_lds_dwordx4 v[6:7], off
	v_lshl_add_u64 v[0:1], v[0:1], 0, s[6:7]
	s_mov_b32 m0, s51
	s_add_u32 s2, s36, 0x40080
	global_load_lds_dwordx4 v[0:1], off
	v_lshl_add_u64 v[0:1], v[2:3], 0, s[6:7]
	s_mov_b32 m0, s52
	s_addc_u32 s3, s37, 0
	global_load_lds_dwordx4 v[0:1], off
	s_add_i32 m0, s46, 0x1c000
	v_lshl_add_u64 v[0:1], s[2:3], 0, v[154:155]
	global_load_lds_dwordx4 v[0:1], off
	v_lshl_add_u64 v[0:1], s[2:3], 0, v[158:159]
	s_add_i32 m0, s46, 0x1e000
	v_and_b32_e32 v3, 32, v4
	global_load_lds_dwordx4 v[0:1], off
	s_cselect_b32 s100, 1, 0
	s_cmp_eq_u32 s101, 0
	s_cbranch_scc1 .Lpk1_HGOUT
	s_barrier
.Lpk1_HGOUT:
	s_waitcnt vmcnt(8)
	s_barrier
	s_cmp_lg_u32 s100, 0
	v_bfe_u32 v0, v24, 4, 2
	v_lshlrev_b32_e32 v2, 4, v0
	v_lshl_or_b32 v2, v31, 6, v2
	v_lshl_or_b32 v184, s0, 6, v31
	v_lshlrev_b32_e32 v1, 3, v0
	v_bitop3_b32 v4, v2, s1, v3 bitop3:0xde
	v_cmp_eq_u32_e64 s[0:1], 0, v0
	v_lshlrev_b32_e32 v0, 14, v25
	v_and_b32_e32 v0, 0xffff8000, v0
	v_lshl_or_b32 v186, s50, 5, v1
	v_lshl_add_u32 v0, v26, 11, v0
	v_and_b32_e32 v1, 1, v25
	v_lshl_or_b32 v0, v1, 6, v0
	v_lshl_add_u32 v160, v27, 1, v0
	v_lshlrev_b32_e32 v0, 14, v28
	v_and_b32_e32 v0, 0xffff8000, v0
	v_lshl_add_u32 v0, v29, 11, v0
	v_and_b32_e32 v1, 1, v28
	s_waitcnt vmcnt(6)
	v_lshl_or_b32 v0, v1, 6, v0
	v_bitop3_b32 v185, v2, s9, v3 bitop3:0xde
	v_mov_b32_e32 v161, 0
	v_lshl_add_u32 v162, v30, 1, v0
	s_add_i32 s55, 0, 0x10000
	s_add_i32 s56, 0, 0x14000
	v_mbcnt_lo_u32_b32 v0, -1, 0
	s_mov_b32 s9, 0
	s_ashr_i32 s53, s17, 31
	s_ashr_i32 s54, s16, 31
	v_mov_b32_e32 v163, v161
	v_mov_b64_e32 v[164:165], 0x100
	v_mov_b64_e32 v[166:167], 0xff
	v_add_u32_e32 v187, s55, v185
	v_add_u32_e32 v188, s56, v185
	v_add_u32_e32 v189, 0, v4
	v_mbcnt_hi_u32_b32 v190, -1, v0
	s_mov_b32 s57, 0
	s_barrier
	s_branch .LBB0_1523

.LBB0_1641:
	v_ashrrev_i32_e32 v1, 31, v30
	v_lshrrev_b32_e32 v1, 26, v1
	v_add_u32_e32 v1, v30, v1
	v_ashrrev_i32_e32 v10, 6, v1
	v_bfe_i32 v1, v30, 27, 1
	v_lshlrev_b32_e32 v0, 4, v30
	v_lshrrev_b32_e32 v1, 22, v1
	v_add_u32_e32 v1, v0, v1
	v_and_b32_e32 v1, 0xfffffc00, v1
	v_sub_u32_e32 v1, v0, v1
	v_lshrrev_b32_e32 v2, 4, v1
	v_bitop3_b32 v1, v2, v1, 32 bitop3:0x6c
	v_ashrrev_i32_e32 v3, 31, v1
	v_lshrrev_b32_e32 v3, 26, v3
	v_add_u32_e32 v3, v1, v3
	v_lshlrev_b32_e32 v2, 3, v10
	v_ashrrev_i32_e32 v11, 6, v3
	v_and_b32_e32 v3, 0xc0, v3
	v_and_b32_e32 v2, -16, v2
	v_sub_u32_e32 v1, v1, v3
	v_mov_b32_e32 v3, 1
	v_add_u32_e32 v2, v11, v2
	v_ashrrev_i16_sdwa v1, v3, sext(v1) dst_sel:DWORD dst_unused:UNUSED_PAD src0_sel:DWORD src1_sel:BYTE_0
	v_bfe_i32 v12, v1, 0, 16
	v_lshlrev_b32_e32 v1, 1, v2
	v_lshlrev_b32_e32 v6, 5, v10
	v_and_b32_e32 v13, 0x1fffe0, v2
	v_and_b32_e32 v14, 24, v1
	v_lshrrev_b32_e32 v1, 2, v2
	v_and_b32_e32 v16, 3, v11
	v_and_b32_e32 v6, 32, v6
	v_and_b32_e32 v15, 4, v1
	v_or_b32_e32 v1, v13, v16
	v_or3_b32 v1, v1, v15, v14
	v_add_lshl_u32 v6, v6, v12, 1
	v_add_u32_e32 v0, 0x2000, v0
	v_lshl_add_u32 v130, v1, 11, v6
	v_ashrrev_i32_e32 v1, 31, v0
	v_lshrrev_b32_e32 v1, 22, v1
	v_add_u32_e32 v1, v0, v1
	v_ashrrev_i32_e32 v17, 10, v1
	v_mul_i32_i24_e32 v1, 0x400, v17
	v_sub_u32_e32 v0, v0, v1
	v_lshrrev_b32_e32 v1, 4, v0
	v_bitop3_b32 v0, v1, v0, 32 bitop3:0x6c
	v_lshl_add_u32 v128, v2, 11, v6
	v_ashrrev_i32_e32 v2, 31, v0
	s_ashr_i32 s12, s6, 6
	s_ashr_i32 s7, s6, 8
	v_lshrrev_b32_e32 v2, 26, v2
	s_lshl_b32 s25, s12, 10
	v_add_u32_e32 v2, v0, v2
	s_add_u32 s37, s28, 0x2800000
	v_lshlrev_b32_e32 v1, 3, v17
	v_ashrrev_i32_e32 v6, 6, v2
	v_and_b32_e32 v2, 0xc0, v2
	s_addc_u32 s52, s29, 0
	s_lshl_b32 s4, s84, 8
	s_lshl_b32 s2, s79, 8
	v_and_b32_e32 v1, -16, v1
	v_sub_u32_e32 v0, v0, v2
	s_ashr_i32 s5, s4, 31
	s_ashr_i32 s3, s2, 31
	v_add_u32_e32 v1, v6, v1
	v_ashrrev_i16_sdwa v0, v3, sext(v0) dst_sel:DWORD dst_unused:UNUSED_PAD src0_sel:DWORD src1_sel:BYTE_0
	s_lshl_b64 s[10:11], s[4:5], 11
	s_lshl_b64 s[14:15], s[2:3], 11
	v_bfe_i32 v18, v0, 0, 16
	v_lshlrev_b32_e32 v0, 1, v1
	s_add_u32 s50, s37, s14
	v_lshlrev_b32_e32 v7, 5, v17
	v_and_b32_e32 v19, 0x1fffe0, v1
	v_and_b32_e32 v20, 24, v0
	v_lshrrev_b32_e32 v0, 2, v1
	v_and_b32_e32 v22, 3, v6
	s_addc_u32 s51, s52, s15
	s_add_i32 s53, s25, 0
	v_and_b32_e32 v7, 32, v7
	v_and_b32_e32 v21, 4, v0
	v_or_b32_e32 v0, v19, v22
	s_add_i32 m0, s53, 0x10000
	v_or3_b32 v0, v0, v21, v20
	v_add_lshl_u32 v2, v7, v18, 1
	global_load_lds_dwordx4 v130, s[50:51]
	s_add_i32 m0, s53, 0x12000
	v_lshl_add_u32 v134, v0, 11, v2
	s_add_u32 s14, s50, 0x40000
	global_load_lds_dwordx4 v134, s[50:51]
	s_addc_u32 s15, s51, 0
	s_add_i32 m0, s53, 0x14000
	v_lshl_add_u32 v132, v1, 11, v2
	global_load_lds_dwordx4 v130, s[14:15]
	s_add_i32 m0, s53, 0x16000
	s_add_u32 s48, s34, s10
	s_addc_u32 s49, s35, s11
	s_add_i32 s60, s53, 0x2000
	global_load_lds_dwordx4 v134, s[14:15]
	s_mov_b32 m0, s53
	s_add_u32 s10, s48, 0x40000
	global_load_lds_dwordx4 v128, s[48:49]
	s_mov_b32 m0, s60
	s_addc_u32 s11, s49, 0
	s_add_i32 s61, s53, 0x4000
	global_load_lds_dwordx4 v132, s[48:49]
	s_mov_b32 m0, s61
	s_add_i32 s62, s53, 0x6000
	global_load_lds_dwordx4 v128, s[10:11]
	s_mov_b32 m0, s62
	v_mov_b32_e32 v131, 0
	global_load_lds_dwordx4 v132, s[10:11]
	v_mov_b32_e32 v135, v131
	v_mov_b32_e32 v129, v131
	v_mov_b32_e32 v133, v131
	s_cmp_eq_u32 s7, 1
	s_mov_b32 s54, 0
	v_lshl_add_u64 v[8:9], s[50:51], 0, v[130:131]
	v_lshl_add_u64 v[6:7], s[50:51], 0, v[134:135]
	v_lshl_add_u64 v[0:1], s[48:49], 0, v[128:129]
	s_cselect_b64 s[10:11], -1, 0
	s_cmp_lg_u32 s7, 1
	v_lshl_add_u64 v[2:3], s[48:49], 0, v[132:133]
	s_cselect_b32 s101, 0, 1

.LBB0_1643:
	s_lshl_b32 s5, s12, 5
	s_and_b32 s5, s5, 0x60
	s_lshl_b32 s3, s7, 13
	s_lshl_b32 s24, s5, 7
	s_add_u32 s12, s28, 0x4300000
	s_mov_b64 s[14:15], 0x80
	s_addc_u32 s13, s29, 0
	s_add_i32 m0, s53, 0x18000
	v_lshl_add_u64 v[8:9], v[8:9], 0, s[14:15]


	global_load_lds_dwordx4 v[8:9], off
	v_lshl_add_u64 v[6:7], v[6:7], 0, s[14:15]
	s_add_i32 m0, s53, 0x1a000
	s_add_i32 s63, s53, 0x8000
	s_add_i32 s64, s53, 0xa000
	global_load_lds_dwordx4 v[6:7], off
	v_lshl_add_u64 v[0:1], v[0:1], 0, s[14:15]
	s_mov_b32 m0, s63
	s_add_u32 s18, s50, 0x40080
	global_load_lds_dwordx4 v[0:1], off
	v_lshl_add_u64 v[0:1], v[2:3], 0, s[14:15]
	s_mov_b32 m0, s64
	s_addc_u32 s19, s51, 0
	global_load_lds_dwordx4 v[0:1], off
	s_add_i32 m0, s53, 0x1c000
	v_lshl_add_u64 v[0:1], s[18:19], 0, v[130:131]
	global_load_lds_dwordx4 v[0:1], off
	v_lshl_add_u64 v[0:1], s[18:19], 0, v[134:135]
	s_add_i32 m0, s53, 0x1e000
	v_bfe_u32 v2, v5, 4, 2
	global_load_lds_dwordx4 v[0:1], off
	s_cselect_b32 s100, 1, 0
	s_cmp_eq_u32 s101, 0
	s_cbranch_scc1 .Lpk1_GATE1
	s_barrier
.Lpk1_GATE1:
	s_waitcnt vmcnt(8)
	s_barrier
	s_cmp_lg_u32 s100, 0
	v_lshl_or_b32 v163, s7, 6, v4
	v_lshlrev_b32_e32 v0, 4, v2
	v_lshlrev_b32_e32 v1, 6, v4
	s_movk_i32 s7, 0x3c0
	v_lshlrev_b32_e32 v4, 2, v4
	v_and_or_b32 v3, v1, s7, v0
	v_and_b32_e32 v4, 32, v4
	v_or_b32_e32 v1, v0, v1
	v_bitop3_b32 v167, s24, v1, v4 bitop3:0xf6
	v_mov_b32_e32 v1, v131
	v_lshl_add_u64 v[136:137], s[74:75], 0, v[0:1]
	v_add_u32_e32 v0, v13, v14
	v_and_b32_e32 v1, 1, v10
	v_add3_u32 v0, v0, v15, v16
	v_lshlrev_b32_e32 v1, 6, v1
	v_lshl_or_b32 v168, v2, 3, s5
	v_lshl_or_b32 v0, v0, 11, v1
	v_lshlrev_b32_e32 v2, 1, v12
	v_bitop3_b32 v3, v3, s3, v4 bitop3:0xde
	v_add_u32_e32 v138, v0, v2
	v_add_u32_e32 v0, v19, v20
	v_and_b32_e32 v4, 1, v17
	s_cmpk_lt_u32 s6, 0x100
	v_add3_u32 v0, v0, v21, v22
	v_lshlrev_b32_e32 v4, 6, v4
	s_cselect_b64 s[18:19], -1, 0
	s_and_b32 s3, s16, 7
	s_ashr_i32 s67, s16, 3
	v_lshl_or_b32 v0, v0, 11, v4
	s_lshl_b32 s5, s3, 3
	s_and_b32 s6, s67, 7
	v_lshl_add_u32 v140, v18, 1, v0
	v_lshlrev_b32_e32 v0, 14, v10
	s_or_b32 s68, s5, s6
	s_lshl_b32 s5, s67, 7
	v_and_b32_e32 v0, 0xffff8000, v0
	s_lshl_b32 s3, s3, 11
	s_and_b32 s5, s5, 0x780
	v_lshl_add_u32 v0, v11, 11, v0
	s_waitcnt vmcnt(6)
	s_or_b32 s70, s5, s3
	s_lshr_b32 s3, s16, 7
	v_or_b32_e32 v0, v0, v1
	s_mul_i32 s71, s3, 0x180
	v_add_u32_e32 v142, v0, v2
	s_add_i32 s73, 0, 0x10000
	s_add_i32 s76, 0, 0x14000
	v_mbcnt_lo_u32_b32 v0, -1, 0
	s_ashr_i32 s65, s17, 31
	s_ashr_i32 s66, s16, 31
	s_lshl_b32 s69, s68, 8
	s_addk_i32 s71, 0x800
	s_lshr_b32 s72, s70, 8
	v_mov_b32_e32 v139, v131
	v_mov_b32_e32 v141, v131
	v_mov_b32_e32 v143, v131
	v_add_u32_e32 v169, s73, v167
	v_add_u32_e32 v170, s76, v167
	v_add_u32_e32 v171, 0, v3
	v_add_u32_e32 v172, 0, v167
	s_mov_b32 s24, 0x3a800000
	s_mov_b32 s36, 0x358637bd
	s_mov_b32 s77, 0x800000
	s_movk_i32 s78, 0x1600
	v_mov_b64_e32 v[144:145], 0x2bf
	v_mbcnt_hi_u32_b32 v173, -1, v0
	s_mov_b32 s46, 0
	s_barrier
	s_branch .LBB0_1646

.LBB0_1731:
	s_andn2_b64 vcc, exec, s[6:7]
	s_cbranch_vccnz .LBB0_1808
	v_ashrrev_i32_e32 v3, 31, v0
	v_lshrrev_b32_e32 v3, 26, v3
	v_lshlrev_b32_e32 v2, 4, v0
	v_add_u32_e32 v3, v0, v3
	v_bfe_i32 v0, v0, 27, 1
	v_lshrrev_b32_e32 v0, 22, v0
	v_add_u32_e32 v0, v2, v0
	v_and_b32_e32 v0, 0xfffffc00, v0
	v_sub_u32_e32 v0, v2, v0
	v_ashrrev_i32_e32 v10, 6, v3
	v_lshrrev_b32_e32 v3, 4, v0
	v_bitop3_b32 v0, v3, v0, 32 bitop3:0x6c
	v_ashrrev_i32_e32 v4, 31, v0
	v_lshrrev_b32_e32 v4, 26, v4
	v_add_u32_e32 v4, v0, v4
	v_lshlrev_b32_e32 v3, 3, v10
	v_ashrrev_i32_e32 v11, 6, v4
	v_and_b32_e32 v4, 0xc0, v4
	v_and_b32_e32 v3, -16, v3
	v_sub_u32_e32 v0, v0, v4
	v_mov_b32_e32 v4, 1
	v_add_u32_e32 v3, v11, v3
	v_ashrrev_i16_sdwa v0, v4, sext(v0) dst_sel:DWORD dst_unused:UNUSED_PAD src0_sel:DWORD src1_sel:BYTE_0
	v_bfe_i32 v12, v0, 0, 16
	v_lshlrev_b32_e32 v0, 1, v3
	v_lshlrev_b32_e32 v5, 5, v10
	v_and_b32_e32 v13, 0x1fffe0, v3
	v_and_b32_e32 v14, 24, v0
	v_lshrrev_b32_e32 v0, 2, v3
	v_and_b32_e32 v16, 3, v11
	v_and_b32_e32 v5, 32, v5
	v_and_b32_e32 v15, 4, v0
	v_or_b32_e32 v0, v13, v16
	v_or3_b32 v0, v0, v15, v14
	v_add_lshl_u32 v5, v5, v12, 1
	v_lshl_add_u32 v184, v0, 11, v5
	v_add_u32_e32 v0, 0x2000, v2
	v_ashrrev_i32_e32 v2, 31, v0
	v_lshrrev_b32_e32 v2, 22, v2
	v_add_u32_e32 v2, v0, v2
	v_ashrrev_i32_e32 v17, 10, v2
	v_mul_i32_i24_e32 v2, 0x400, v17
	v_sub_u32_e32 v0, v0, v2
	v_lshrrev_b32_e32 v2, 4, v0
	v_bitop3_b32 v0, v2, v0, 32 bitop3:0x6c
	v_lshl_add_u32 v182, v3, 11, v5
	v_ashrrev_i32_e32 v3, 31, v0
	v_lshrrev_b32_e32 v3, 26, v3
	v_add_u32_e32 v3, v0, v3
	s_add_u32 s45, s28, 0x2d80000
	v_lshlrev_b32_e32 v2, 3, v17
	v_ashrrev_i32_e32 v5, 6, v3
	v_and_b32_e32 v3, 0xc0, v3
	s_addc_u32 s47, s29, 0
	v_and_b32_e32 v2, -16, v2
	v_sub_u32_e32 v0, v0, v3
	s_ashr_i32 s1, s40, 6
	s_ashr_i32 s5, s4, 31
	s_ashr_i32 s3, s2, 31
	s_ashr_i32 s0, s40, 8
	v_add_u32_e32 v2, v5, v2
	v_ashrrev_i16_sdwa v0, v4, sext(v0) dst_sel:DWORD dst_unused:UNUSED_PAD src0_sel:DWORD src1_sel:BYTE_0
	s_lshl_b32 s70, s1, 10
	s_lshl_b64 s[6:7], s[4:5], 11
	s_lshl_b64 s[8:9], s[2:3], 11
	v_bfe_i32 v18, v0, 0, 16
	v_lshlrev_b32_e32 v0, 1, v2
	s_add_u32 s60, s45, s8
	v_lshlrev_b32_e32 v6, 5, v17
	v_and_b32_e32 v19, 0x1fffe0, v2
	v_and_b32_e32 v20, 24, v0
	v_lshrrev_b32_e32 v0, 2, v2
	v_and_b32_e32 v22, 3, v5
	s_addc_u32 s61, s47, s9
	s_add_i32 s71, s70, 0
	v_and_b32_e32 v6, 32, v6
	v_and_b32_e32 v21, 4, v0
	v_or_b32_e32 v0, v19, v22
	s_add_i32 m0, s71, 0x10000
	v_or3_b32 v0, v0, v21, v20
	v_add_lshl_u32 v3, v6, v18, 1
	global_load_lds_dwordx4 v184, s[60:61]
	s_add_i32 m0, s71, 0x12000
	v_lshl_add_u32 v188, v0, 11, v3
	s_add_u32 s8, s60, 0x40000
	global_load_lds_dwordx4 v188, s[60:61]
	s_addc_u32 s9, s61, 0
	s_add_i32 m0, s71, 0x14000
	v_lshl_add_u32 v186, v2, 11, v3
	global_load_lds_dwordx4 v184, s[8:9]
	s_add_i32 m0, s71, 0x16000
	v_mov_b32_e32 v0, 0
	global_load_lds_dwordx4 v188, s[8:9]
	s_add_u32 s8, s34, s6
	s_addc_u32 s9, s35, s7
	s_add_i32 s76, s71, 0x2000
	s_mov_b32 m0, s71
	s_add_u32 s6, s8, 0x40000
	global_load_lds_dwordx4 v182, s[8:9]
	s_mov_b32 m0, s76
	s_addc_u32 s7, s9, 0
	s_add_i32 s77, s71, 0x4000
	global_load_lds_dwordx4 v186, s[8:9]
	s_mov_b32 m0, s77
	s_add_i32 s78, s71, 0x6000
	global_load_lds_dwordx4 v182, s[6:7]
	s_mov_b32 m0, s78
	v_mov_b32_e32 v185, v0
	global_load_lds_dwordx4 v186, s[6:7]
	v_mov_b32_e32 v189, v0
	v_mov_b32_e32 v183, v0
	v_mov_b32_e32 v187, v0
	s_cmp_eq_u32 s0, 1
	s_mov_b32 s62, 0
	v_lshl_add_u64 v[8:9], s[60:61], 0, v[184:185]
	v_lshl_add_u64 v[6:7], s[60:61], 0, v[188:189]
	v_lshl_add_u64 v[2:3], s[8:9], 0, v[182:183]
	s_cselect_b64 s[14:15], -1, 0
	s_cmp_lg_u32 s0, 1
	v_lshl_add_u64 v[4:5], s[8:9], 0, v[186:187]
	s_cselect_b32 s101, 0, 1

.LBB0_1734:
	s_add_u32 s18, s20, 0x8400
	s_addc_u32 s19, s21, 0
	s_add_u32 s22, s22, 0x2c00
	s_addc_u32 s23, s23, 0
	s_add_u32 s24, s28, 0x4300000
	s_addc_u32 s25, s29, 0
	s_add_u32 s36, s28, 0x9b00000
	s_addc_u32 s37, s29, 0
	s_lshl_b32 s1, s1, 5
	s_mov_b64 s[38:39], 0x80
	s_and_b32 s1, s1, 0x60
	s_add_i32 m0, s71, 0x18000
	v_lshl_add_u64 v[8:9], v[8:9], 0, s[38:39]
	s_lshl_b32 s3, s0, 13
	s_lshl_b32 s5, s1, 7


	global_load_lds_dwordx4 v[8:9], off
	v_lshl_add_u64 v[6:7], v[6:7], 0, s[38:39]
	s_add_i32 m0, s71, 0x1a000
	s_add_i32 s79, s71, 0x8000
	s_add_i32 s80, s71, 0xa000
	global_load_lds_dwordx4 v[6:7], off
	v_lshl_add_u64 v[2:3], v[2:3], 0, s[38:39]
	s_mov_b32 m0, s79
	s_add_u32 s6, s60, 0x40080
	global_load_lds_dwordx4 v[2:3], off
	v_lshl_add_u64 v[2:3], v[4:5], 0, s[38:39]
	s_mov_b32 m0, s80
	s_addc_u32 s7, s61, 0
	global_load_lds_dwordx4 v[2:3], off
	s_add_i32 m0, s71, 0x1c000
	v_lshl_add_u64 v[2:3], s[6:7], 0, v[184:185]
	global_load_lds_dwordx4 v[2:3], off
	v_lshl_add_u64 v[2:3], s[6:7], 0, v[188:189]
	s_add_i32 m0, s71, 0x1e000
	v_bfe_u32 v4, v1, 4, 2
	global_load_lds_dwordx4 v[2:3], off
	s_cselect_b32 s100, 1, 0
	s_cmp_eq_u32 s101, 0
	s_cbranch_scc1 .Lpk1_UP1
	s_barrier
.Lpk1_UP1:
	s_waitcnt vmcnt(8)
	s_barrier
	s_cmp_lg_u32 s100, 0
	v_and_b32_e32 v3, 15, v1
	v_lshlrev_b32_e32 v2, 4, v4
	v_lshlrev_b32_e32 v1, 2, v1
	v_lshl_or_b32 v240, s0, 6, v3
	v_lshl_or_b32 v5, v3, 6, v2
	v_and_b32_e32 v1, 32, v1
	s_cmpk_lt_u32 s40, 0x100
	v_lshl_or_b32 v242, v4, 3, s1
	v_cmp_lt_u32_e64 s[0:1], 13, v3
	v_mov_b32_e32 v3, v0
	v_bitop3_b32 v6, v5, s3, v1 bitop3:0xde
	v_bitop3_b32 v241, s5, v5, v1 bitop3:0xf6
	s_cselect_b64 s[40:41], -1, 0
	s_and_b32 s3, s16, 7
	s_ashr_i32 s83, s16, 3
	v_lshl_add_u64 v[190:191], s[74:75], 0, v[2:3]
	v_add_u32_e32 v1, v13, v14
	v_and_b32_e32 v2, 1, v10
	s_lshl_b32 s5, s3, 3
	s_and_b32 s6, s83, 7
	v_add3_u32 v1, v1, v15, v16
	v_lshlrev_b32_e32 v2, 6, v2
	s_or_b32 s84, s5, s6
	s_lshl_b32 s5, s83, 7
	v_lshl_or_b32 v1, v1, 11, v2
	v_lshlrev_b32_e32 v3, 1, v12
	s_lshl_b32 s3, s3, 11
	s_and_b32 s5, s5, 0x780
	v_add_u32_e32 v192, v1, v3
	v_add_u32_e32 v1, v19, v20
	v_and_b32_e32 v4, 1, v17
	s_or_b32 s86, s5, s3
	s_lshr_b32 s3, s16, 7
	v_add3_u32 v1, v1, v21, v22
	v_lshlrev_b32_e32 v4, 6, v4
	s_mul_i32 s87, s3, 0x180
	v_lshl_or_b32 v1, v1, 11, v4
	s_ashr_i32 s81, s17, 31
	s_ashr_i32 s82, s16, 31
	s_lshl_b32 s85, s84, 8
	s_addk_i32 s87, 0x800
	s_lshr_b32 s88, s86, 8
	v_lshl_add_u32 v194, v18, 1, v1
	v_lshlrev_b32_e32 v1, 14, v10
	s_add_u32 s42, s20, 0xb000
	v_and_b32_e32 v1, 0xffff8000, v1
	s_addc_u32 s43, s21, 0
	v_lshl_add_u32 v1, v11, 11, v1
	s_waitcnt vmcnt(6)
	s_add_u32 s20, s20, 0xdc00
	v_or_b32_e32 v1, v1, v2
	s_addc_u32 s21, s21, 0
	v_add_u32_e32 v196, v1, v3
	s_add_i32 s74, 0, 0x10000
	s_add_i32 s75, 0, 0x14000
	v_mbcnt_lo_u32_b32 v1, -1, 0
	v_mov_b32_e32 v193, v0
	v_mov_b32_e32 v195, v0
	v_mov_b32_e32 v197, v0
	v_add_u32_e32 v243, s74, v241
	v_add_u32_e32 v244, s75, v241
	v_add_u32_e32 v245, 0, v6
	v_add_u32_e32 v246, 0, v241
	s_movk_i32 s89, 0x1600
	v_mov_b32_e32 v247, 0x358637bd
	s_mov_b32 s44, 0x3a800000
	s_mov_b32 s90, 0x800000
	s_mov_b32 s46, 0x358637bd
	v_mbcnt_hi_u32_b32 v248, -1, v1
	s_mov_b32 s55, 0
	s_barrier
	s_branch .LBB0_1737

.LBB0_1867:
	v_ashrrev_i32_e32 v2, 31, v0
	v_lshrrev_b32_e32 v2, 26, v2
	s_waitcnt lgkmcnt(0)
	v_lshlrev_b32_e32 v1, 4, v0
	v_add_u32_e32 v2, v0, v2
	v_bfe_i32 v0, v0, 27, 1
	v_lshrrev_b32_e32 v0, 22, v0
	v_add_u32_e32 v0, v1, v0
	v_and_b32_e32 v0, 0xfffffc00, v0
	v_sub_u32_e32 v0, v1, v0
	v_ashrrev_i32_e32 v9, 6, v2
	v_lshrrev_b32_e32 v2, 4, v0
	v_bitop3_b32 v0, v2, v0, 32 bitop3:0x6c
	v_ashrrev_i32_e32 v3, 31, v0
	v_lshrrev_b32_e32 v3, 26, v3
	v_lshlrev_b32_e32 v2, 3, v9
	v_add_u32_e32 v3, v0, v3
	v_and_b32_e32 v2, -16, v2
	v_ashrrev_i32_e32 v11, 6, v3
	v_and_b32_e32 v3, 0xc0, v3
	v_add_u32_e32 v2, v11, v2
	v_lshlrev_b32_e32 v4, 5, v9
	v_sub_u32_e32 v0, v0, v3
	v_mov_b32_e32 v3, 1
	v_and_b32_e32 v10, 32, v4
	v_ashrrev_i16_sdwa v0, v3, sext(v0) dst_sel:DWORD dst_unused:UNUSED_PAD src0_sel:DWORD src1_sel:BYTE_0
	v_lshlrev_b32_e32 v4, 1, v2
	v_lshrrev_b32_e32 v5, 2, v2
	v_and_b32_e32 v6, 3, v11
	s_mov_b32 s6, 0xffffe0
	v_bfe_i32 v12, v0, 0, 16
	v_and_b32_e32 v4, 24, v4
	v_and_b32_e32 v5, 4, v5
	v_and_or_b32 v6, v2, s6, v6
	s_movk_i32 s4, 0xb00
	v_add_u32_e32 v0, v10, v12
	v_or3_b32 v4, v6, v5, v4
	v_mul_lo_u32 v2, v2, s4
	v_add_lshl_u32 v156, v0, v2, 1
	v_mul_u32_u24_e32 v2, 0xb00, v4
	v_add_lshl_u32 v158, v2, v0, 1
	v_add_u32_e32 v0, 0x2000, v1
	v_ashrrev_i32_e32 v1, 31, v0
	v_lshrrev_b32_e32 v1, 22, v1
	v_add_u32_e32 v1, v0, v1
	v_ashrrev_i32_e32 v13, 10, v1
	v_mul_i32_i24_e32 v1, 0x400, v13
	v_sub_u32_e32 v0, v0, v1
	v_lshrrev_b32_e32 v1, 4, v0
	v_bitop3_b32 v0, v1, v0, 32 bitop3:0x6c
	s_add_u32 s31, s28, 0x9b00000
	v_ashrrev_i32_e32 v2, 31, v0
	s_addc_u32 s33, s29, 0
	v_lshrrev_b32_e32 v2, 26, v2
	s_add_u32 s36, s28, 0x3300000
	v_lshlrev_b32_e32 v1, 3, v13
	v_add_u32_e32 v2, v0, v2
	s_addc_u32 s37, s29, 0
	s_ashr_i32 s5, s30, 6
	v_and_b32_e32 v1, -16, v1
	v_ashrrev_i32_e32 v14, 6, v2
	v_and_b32_e32 v2, 0xc0, v2
	v_add_u32_e32 v1, v14, v1
	v_lshlrev_b32_e32 v4, 5, v13
	v_sub_u32_e32 v0, v0, v2
	s_ashr_i32 s8, s30, 8
	s_lshl_b32 s38, s5, 10
	v_and_b32_e32 v15, 32, v4
	v_ashrrev_i16_sdwa v0, v3, sext(v0) dst_sel:DWORD dst_unused:UNUSED_PAD src0_sel:DWORD src1_sel:BYTE_0
	v_lshlrev_b32_e32 v2, 1, v1
	v_lshrrev_b32_e32 v3, 2, v1
	v_and_b32_e32 v4, 3, v14
	s_add_u32 s24, s36, s2
	v_bfe_i32 v16, v0, 0, 16
	v_and_b32_e32 v2, 24, v2
	v_and_b32_e32 v3, 4, v3
	v_and_or_b32 v4, v1, s6, v4
	s_addc_u32 s25, s37, s3
	s_add_i32 s39, s38, 0
	v_add_u32_e32 v0, v15, v16
	v_or3_b32 v2, v4, v3, v2
	v_mul_lo_u32 v1, v1, s4
	s_add_i32 m0, s39, 0x10000
	v_add_lshl_u32 v160, v0, v1, 1
	v_mul_u32_u24_e32 v1, 0xb00, v2
	global_load_lds_dwordx4 v158, s[24:25]
	s_add_i32 m0, s39, 0x12000
	v_add_lshl_u32 v162, v1, v0, 1
	s_add_u32 s2, s24, 0xb0000
	global_load_lds_dwordx4 v162, s[24:25]
	s_addc_u32 s3, s25, 0
	s_add_i32 m0, s39, 0x14000
	v_mov_b32_e32 v159, 0
	global_load_lds_dwordx4 v158, s[2:3]
	s_add_i32 m0, s39, 0x16000
	s_add_u32 s22, s31, s0
	s_addc_u32 s23, s33, s1
	s_add_i32 s40, s39, 0x2000
	global_load_lds_dwordx4 v162, s[2:3]
	s_mov_b32 m0, s39
	s_add_u32 s0, s22, 0xb0000
	global_load_lds_dwordx4 v156, s[22:23]
	s_mov_b32 m0, s40
	s_addc_u32 s1, s23, 0
	s_add_i32 s41, s39, 0x4000
	global_load_lds_dwordx4 v160, s[22:23]
	s_mov_b32 m0, s41
	s_add_i32 s42, s39, 0x6000
	global_load_lds_dwordx4 v156, s[0:1]
	s_mov_b32 m0, s42
	v_mov_b32_e32 v163, v159
	global_load_lds_dwordx4 v160, s[0:1]
	v_mov_b32_e32 v157, v159
	v_mov_b32_e32 v161, v159
	s_mov_b32 s43, 0
	v_lshl_add_u64 v[6:7], s[24:25], 0, v[158:159]
	v_lshl_add_u64 v[4:5], s[24:25], 0, v[162:163]
	v_lshl_add_u64 v[2:3], s[22:23], 0, v[156:157]
	s_cmp_lg_u32 s8, 1
	v_lshl_add_u64 v[0:1], s[22:23], 0, v[160:161]
	s_cselect_b32 s101, 0, 1

.LBB0_1869:
	s_mov_b64 s[6:7], 0x80
	s_and_b32 s2, s5, 3
	s_add_i32 m0, s39, 0x18000
	v_lshl_add_u64 v[6:7], v[6:7], 0, s[6:7]
	s_lshl_b32 s3, s8, 13
	s_lshl_b32 s5, s2, 12


	global_load_lds_dwordx4 v[6:7], off
	v_lshl_add_u64 v[4:5], v[4:5], 0, s[6:7]
	s_add_i32 m0, s39, 0x1a000
	s_add_i32 s44, s39, 0x8000
	s_add_i32 s45, s39, 0xa000
	global_load_lds_dwordx4 v[4:5], off
	v_lshl_add_u64 v[2:3], v[2:3], 0, s[6:7]
	s_mov_b32 m0, s44
	s_add_u32 s0, s24, 0xb0080
	global_load_lds_dwordx4 v[2:3], off
	v_lshl_add_u64 v[0:1], v[0:1], 0, s[6:7]
	s_mov_b32 m0, s45
	s_addc_u32 s1, s25, 0
	global_load_lds_dwordx4 v[0:1], off
	s_add_i32 m0, s39, 0x1c000
	v_lshl_add_u64 v[0:1], s[0:1], 0, v[158:159]
	global_load_lds_dwordx4 v[0:1], off
	v_lshl_add_u64 v[0:1], s[0:1], 0, v[162:163]
	s_add_i32 m0, s39, 0x1e000
	s_mov_b64 s[0:1], 0xb0080
	global_load_lds_dwordx4 v[0:1], off
	s_cselect_b32 s100, 1, 0
	s_cmp_eq_u32 s101, 0
	s_cbranch_scc1 .Lpk1_DOWN1
	s_barrier
.Lpk1_DOWN1:
	s_waitcnt vmcnt(8)
	s_barrier
	s_cmp_lg_u32 s100, 0
	v_bfe_u32 v1, v8, 4, 2
	v_and_b32_e32 v0, 15, v8
	v_lshlrev_b32_e32 v2, 3, v1
	v_lshlrev_b32_e32 v1, 4, v1
	v_lshl_or_b32 v200, s8, 6, v0
	v_lshl_or_b32 v0, v0, 6, v1
	v_lshlrev_b32_e32 v1, 2, v8
	v_and_b32_e32 v1, 32, v1
	v_bitop3_b32 v3, v0, s3, v1 bitop3:0xde
	v_bitop3_b32 v201, v0, s5, v1 bitop3:0xde
	v_lshrrev_b32_e32 v1, 1, v9
	v_mul_lo_u32 v0, v11, s4
	s_mov_b32 s5, 0xb000
	v_lshl_or_b32 v202, s2, 5, v2
	v_mad_u64_u32 v[0:1], s[2:3], v1, s5, v[0:1]
	v_or_b32_e32 v0, v0, v10
	v_add_lshl_u32 v0, v0, v12, 1
	v_mov_b32_e32 v1, v159
	v_lshl_add_u64 v[164:165], v[0:1], 0, s[0:1]
	v_lshrrev_b32_e32 v1, 1, v13
	v_mul_lo_u32 v0, v14, s4
	s_ashr_i32 s46, s17, 31
	s_ashr_i32 s47, s16, 31
	v_mad_u64_u32 v[0:1], s[2:3], v1, s5, v[0:1]
	s_waitcnt vmcnt(6)
	s_cmp_lg_u64 s[26:27], 0
	v_or_b32_e32 v0, v0, v15
	s_cselect_b64 s[8:9], -1, 0
	v_add_lshl_u32 v0, v0, v16, 1
	v_mov_b32_e32 v1, v159
	s_add_i32 s48, 0, 0x10000
	s_add_i32 s49, 0, 0x14000
	v_lshl_add_u64 v[166:167], v[0:1], 0, s[0:1]
	v_mov_b64_e32 v[168:169], 0x100
	v_mov_b64_e32 v[170:171], 0xff
	v_add_u32_e32 v203, s48, v201
	v_add_u32_e32 v204, s49, v201
	v_add_u32_e32 v205, 0, v3
	s_mov_b64 s[10:11], 0x20000
	s_mov_b64 s[12:13], 0x24000
	s_mov_b64 s[14:15], 0x28000
	s_mov_b64 s[18:19], 0x2c000
	s_barrier
	s_branch .LBB0_1871
